# tail w_out GEMM: alternate K direction between column-tile passes (snake order) so A-panel re-reads hit cache
# baseline (speedup 1.0000x reference)
.LBB0_527:
	s_lshl_b32 s0, s0, 5
	s_and_b32 s29, s0, 0x60
	s_lshl_b32 s28, s1, 6
	s_lshl_b32 s13, s1, 13
	s_lshl_b32 s16, s29, 7
	s_add_u32 s0, s80, 0x36900080
	s_addc_u32 s1, s81, 0
	s_add_i32 m0, s3, 0x18000
	v_lshl_add_u64 v[14:15], s[0:1], 0, v[182:183]
	s_waitcnt vmcnt(4)
	s_barrier
	global_load_lds_dwordx4 v[14:15], off
	v_lshl_add_u64 v[14:15], s[0:1], 0, v[178:179]
	s_add_i32 m0, s3, 0x1a000
	s_mov_b64 s[0:1], 0x80
	s_add_i32 s30, s3, 0x8000
	s_add_i32 s31, s3, 0xa000
	global_load_lds_dwordx4 v[14:15], off
	v_lshl_add_u64 v[4:5], v[4:5], 0, s[0:1]
	s_mov_b32 m0, s30
	s_add_u32 s14, s80, 0x36940080
	global_load_lds_dwordx4 v[4:5], off
	v_lshl_add_u64 v[2:3], v[2:3], 0, s[0:1]
	s_mov_b32 m0, s31
	s_addc_u32 s15, s81, 0
	global_load_lds_dwordx4 v[2:3], off
	s_add_i32 m0, s3, 0x1c000
	v_lshl_add_u64 v[2:3], s[14:15], 0, v[182:183]
	global_load_lds_dwordx4 v[2:3], off
	v_lshl_add_u64 v[2:3], s[14:15], 0, v[178:179]
	s_add_i32 m0, s3, 0x1e000
	v_bfe_u32 v209, v8, 4, 2
	global_load_lds_dwordx4 v[2:3], off
	v_and_b32_e32 v208, 15, v8
	v_lshlrev_b32_e32 v2, 4, v209
	v_lshlrev_b32_e32 v3, 2, v8
	v_lshl_or_b32 v2, v208, 6, v2
	v_and_b32_e32 v3, 32, v3
	v_bitop3_b32 v4, v2, s13, v3 bitop3:0xde
	v_bitop3_b32 v5, v2, s16, v3 bitop3:0xde
	v_xor_b32_e32 v2, 16, v1
	v_cmp_lt_i32_e32 vcc, v2, v30
	s_lshl_b32 s44, s86, 8
	s_add_u32 s14, s80, s8
	v_cndmask_b32_e32 v2, v1, v2, vcc
	v_lshlrev_b32_e32 v187, 2, v2
	v_xor_b32_e32 v2, 32, v1
	v_cmp_lt_i32_e32 vcc, v2, v30
	v_mov_b32_e32 v3, v183
	s_addc_u32 s15, s81, s9
	v_cndmask_b32_e32 v1, v1, v2, vcc
	v_lshlrev_b32_e32 v189, 2, v1
	v_lshlrev_b32_e32 v1, 14, v11
	v_and_b32_e32 v1, 0xffff8000, v1
	v_lshl_add_u32 v1, v10, 11, v1
	v_and_b32_e32 v2, 1, v11
	v_lshl_or_b32 v1, v2, 6, v1
	v_lshl_add_u32 v2, v12, 1, v1
	v_lshlrev_b32_e32 v1, 14, v6
	v_lshl_add_u64 v[2:3], s[14:15], 0, v[2:3]
	s_mov_b64 s[16:17], 0x40080
	v_and_b32_e32 v1, 0xffff8000, v1
	v_lshl_add_u64 v[192:193], v[2:3], 0, s[16:17]
	v_lshl_add_u32 v1, v7, 11, v1
	v_and_b32_e32 v2, 1, v6
	v_lshl_or_b32 v1, v2, 6, v1
	s_waitcnt vmcnt(6)
	v_lshl_add_u32 v2, v9, 1, v1
	v_mov_b32_e32 v3, v183
	s_add_i32 s45, 0, 0x10000
	s_add_i32 s46, 0, 0x14000
	s_add_i32 s47, 0, 0x18000
	s_add_i32 s48, 0, 0x1c000
	v_lshl_add_u64 v[2:3], s[14:15], 0, v[2:3]
	s_add_i32 s36, s45, s12
	s_add_i32 s38, s46, s12
	s_add_i32 s40, s47, s12
	s_add_i32 s42, s48, s12
	v_lshl_add_u64 v[194:195], v[2:3], 0, s[16:17]
	v_add_u32_e32 v1, s45, v5
	v_add_u32_e32 v210, 0, v4
	s_add_i32 s34, s3, 0xc000
	s_add_i32 s35, s3, 0xe000
	v_add_u32_e32 v211, s46, v5
	s_add_i32 s37, s36, 0x2000
	s_add_i32 s39, s38, 0x2000
	v_add_u32_e32 v212, s47, v5
	v_add_u32_e32 v213, s48, v5
	s_add_i32 s41, s40, 0x2000
	s_add_i32 s43, s42, 0x2000
	s_mov_b64 s[14:15], s[88:89]
	s_barrier
	s_mov_b32 s98, 0
	s_mov_b32 s99, 0x100
	s_mov_b32 s100, 0x700
	s_mov_b32 s101, 0x40080
	s_branch .LBB0_529

.LBB0_529:
	s_mov_b32 s18, s23
	s_mov_b32 s49, s23
	s_add_i32 s23, s23, 1
	s_cmp_lt_u32 s49, 3
	s_cselect_b64 s[16:17], -1, 0
	s_and_b64 s[12:13], s[16:17], exec
	s_cselect_b32 s12, s23, s18
	s_ashr_i32 s13, s12, 31
	s_lshl_b64 s[12:13], s[12:13], 19
	s_add_u32 s12, s88, s12
	s_addc_u32 s13, s89, s13
	s_and_b64 s[16:17], s[16:17], exec
	s_cselect_b32 s50, s13, s15
	s_cselect_b32 s51, s12, s14
	s_and_b32 s52, s98, 0x780
	s_add_u32 s52, s52, s99
	s_add_u32 s52, s14, s52
	v_mov_b32_e32 v2, 0
	s_addc_u32 s53, s15, 0
	s_mov_b32 s54, -2
	s_mov_b64 s[14:15], 0
	s_waitcnt lgkmcnt(0)
	v_mov_b32_e32 v3, v2
	v_mov_b32_e32 v4, v2
	v_mov_b32_e32 v5, v2
	v_mov_b32_e32 v6, v2
	v_mov_b32_e32 v7, v2
	v_mov_b32_e32 v8, v2
	v_mov_b32_e32 v9, v2
	v_mov_b32_e32 v18, v2
	v_mov_b32_e32 v19, v2
	v_mov_b32_e32 v20, v2
	v_mov_b32_e32 v21, v2
	v_mov_b32_e32 v22, v2
	v_mov_b32_e32 v23, v2
	v_mov_b32_e32 v24, v2
	v_mov_b32_e32 v25, v2
	v_mov_b32_e32 v34, v2
	v_mov_b32_e32 v35, v2
	v_mov_b32_e32 v36, v2
	v_mov_b32_e32 v37, v2
	v_mov_b32_e32 v38, v2
	v_mov_b32_e32 v39, v2
	v_mov_b32_e32 v40, v2
	v_mov_b32_e32 v41, v2
	v_mov_b32_e32 v50, v2
	v_mov_b32_e32 v51, v2
	v_mov_b32_e32 v52, v2
	v_mov_b32_e32 v53, v2
	v_mov_b32_e32 v54, v2
	v_mov_b32_e32 v55, v2
	v_mov_b32_e32 v56, v2
	v_mov_b32_e32 v57, v2
	v_mov_b32_e32 v10, v2
	v_mov_b32_e32 v11, v2
	v_mov_b32_e32 v12, v2
	v_mov_b32_e32 v13, v2
	v_mov_b32_e32 v14, v2
	v_mov_b32_e32 v15, v2
	v_mov_b32_e32 v16, v2
	v_mov_b32_e32 v17, v2
	v_mov_b32_e32 v26, v2
	v_mov_b32_e32 v27, v2
	v_mov_b32_e32 v28, v2
	v_mov_b32_e32 v29, v2
	v_mov_b32_e32 v30, v2
	v_mov_b32_e32 v31, v2
	v_mov_b32_e32 v32, v2
	v_mov_b32_e32 v33, v2
	v_mov_b32_e32 v42, v2
	v_mov_b32_e32 v43, v2
	v_mov_b32_e32 v44, v2
	v_mov_b32_e32 v45, v2
	v_mov_b32_e32 v46, v2
	v_mov_b32_e32 v47, v2
	v_mov_b32_e32 v48, v2
	v_mov_b32_e32 v49, v2
	v_mov_b32_e32 v58, v2
	v_mov_b32_e32 v59, v2
	v_mov_b32_e32 v60, v2
	v_mov_b32_e32 v61, v2
	v_mov_b32_e32 v62, v2
	v_mov_b32_e32 v63, v2
	v_mov_b32_e32 v64, v2
	v_mov_b32_e32 v65, v2
	v_mov_b32_e32 v66, v2
	v_mov_b32_e32 v67, v2
	v_mov_b32_e32 v68, v2
	v_mov_b32_e32 v69, v2
	v_mov_b32_e32 v70, v2
	v_mov_b32_e32 v71, v2
	v_mov_b32_e32 v72, v2
	v_mov_b32_e32 v73, v2
	v_mov_b32_e32 v82, v2
	v_mov_b32_e32 v83, v2
	v_mov_b32_e32 v84, v2
	v_mov_b32_e32 v85, v2
	v_mov_b32_e32 v86, v2
	v_mov_b32_e32 v87, v2
	v_mov_b32_e32 v88, v2
	v_mov_b32_e32 v89, v2
	v_mov_b32_e32 v98, v2
	v_mov_b32_e32 v99, v2
	v_mov_b32_e32 v100, v2
	v_mov_b32_e32 v101, v2
	v_mov_b32_e32 v102, v2
	v_mov_b32_e32 v103, v2
	v_mov_b32_e32 v104, v2
	v_mov_b32_e32 v105, v2
	v_mov_b32_e32 v114, v2
	v_mov_b32_e32 v115, v2
	v_mov_b32_e32 v116, v2
	v_mov_b32_e32 v117, v2
	v_mov_b32_e32 v118, v2
	v_mov_b32_e32 v119, v2
	v_mov_b32_e32 v120, v2
	v_mov_b32_e32 v121, v2
	v_mov_b32_e32 v74, v2
	v_mov_b32_e32 v75, v2
	v_mov_b32_e32 v76, v2
	v_mov_b32_e32 v77, v2
	v_mov_b32_e32 v78, v2
	v_mov_b32_e32 v79, v2
	v_mov_b32_e32 v80, v2
	v_mov_b32_e32 v81, v2
	v_mov_b32_e32 v90, v2
	v_mov_b32_e32 v91, v2
	v_mov_b32_e32 v92, v2
	v_mov_b32_e32 v93, v2
	v_mov_b32_e32 v94, v2
	v_mov_b32_e32 v95, v2
	v_mov_b32_e32 v96, v2
	v_mov_b32_e32 v97, v2
	v_mov_b32_e32 v106, v2
	v_mov_b32_e32 v107, v2
	v_mov_b32_e32 v108, v2
	v_mov_b32_e32 v109, v2
	v_mov_b32_e32 v110, v2
	v_mov_b32_e32 v111, v2
	v_mov_b32_e32 v112, v2
	v_mov_b32_e32 v113, v2
	v_mov_b32_e32 v122, v2
	v_mov_b32_e32 v123, v2
	v_mov_b32_e32 v124, v2
	v_mov_b32_e32 v125, v2
	v_mov_b32_e32 v126, v2
	v_mov_b32_e32 v127, v2
	v_mov_b32_e32 v128, v2
	v_mov_b32_e32 v129, v2
.LBB0_530:
	s_add_u32 s16, s6, s14
	ds_read_b128 v[130:133], v1
	ds_read_b128 v[134:137], v1 offset:1024
	ds_read_b128 v[138:141], v1 offset:2048
	ds_read_b128 v[142:145], v1 offset:3072
	s_addc_u32 s17, s7, s15
	s_add_u32 s16, s16, s99
	s_addc_u32 s17, s17, s98
	s_add_u32 s55, s52, s14
	s_addc_u32 s56, s53, s15
	s_cmp_eq_u32 s14, s100
	s_cselect_b32 s19, s7, s17
	s_cselect_b32 s18, s6, s16
	s_cselect_b32 s17, s50, s56
	s_cselect_b32 s16, s51, s55
	s_mov_b32 m0, s34
	v_lshl_add_u64 v[196:197], v[192:193], 0, s[14:15]
	ds_read_b128 v[146:149], v210
	ds_read_b128 v[150:153], v210 offset:1024
	ds_read_b128 v[154:157], v210 offset:2048
	ds_read_b128 v[158:161], v210 offset:3072
	ds_read_b128 v[162:165], v210 offset:4096
	ds_read_b128 v[166:169], v210 offset:5120
	ds_read_b128 v[170:173], v210 offset:6144
	ds_read_b128 v[174:177], v210 offset:7168
	global_load_lds_dwordx4 v[196:197], off
	v_lshl_add_u64 v[196:197], v[194:195], 0, s[14:15]
	s_mov_b32 m0, s35
	s_nop 0
	global_load_lds_dwordx4 v[196:197], off
	s_cmp_eq_u32 s14, s100
	s_cbranch_scc0 .Lmy_sn2_skip
	s_xor_b32 s56, 0x780, s98
	s_sub_u32 s56, s56, s98
	s_add_u32 s6, s6, s56
	s_addc_u32 s7, s7, s98
	s_xor_b32 s56, 0x680, s98
	s_sub_u32 s56, s56, s98
	s_mov_b32 s57, s98
	v_lshl_add_u64 v[192:193], v[192:193], 0, s[56:57]
	v_lshl_add_u64 v[194:195], v[194:195], 0, s[56:57]
	s_not_b32 s98, s98
	s_sub_i32 s99, 0, s99
	s_sub_i32 s100, 0, s100
	s_sub_i32 s101, 0x80000, s101
	s_sub_u32 s0, 0, s0
	s_subb_u32 s1, 0, s1
	s_mov_b64 s[18:19], s[6:7]
	s_and_b32 s56, s98, 0x780
	s_add_u32 s16, s51, s56
	s_addc_u32 s17, s50, 0
.Lmy_sn2_skip:
	s_waitcnt lgkmcnt(8)
	s_barrier
	s_waitcnt lgkmcnt(0)
	s_setprio 1
	s_waitcnt lgkmcnt(0)
	v_mfma_f32_16x16x32_bf16 v[126:129], v[130:133], v[146:149], v[126:129]
	v_mfma_f32_16x16x32_bf16 v[122:125], v[138:141], v[146:149], v[122:125]
	v_mfma_f32_16x16x32_bf16 v[110:113], v[130:133], v[154:157], v[110:113]
	v_mfma_f32_16x16x32_bf16 v[106:109], v[138:141], v[154:157], v[106:109]
	v_mfma_f32_16x16x32_bf16 v[94:97], v[130:133], v[162:165], v[94:97]
	v_mfma_f32_16x16x32_bf16 v[90:93], v[138:141], v[162:165], v[90:93]
	v_mfma_f32_16x16x32_bf16 v[78:81], v[130:133], v[170:173], v[78:81]
	v_mfma_f32_16x16x32_bf16 v[74:77], v[138:141], v[170:173], v[74:77]
	v_mfma_f32_16x16x32_bf16 v[126:129], v[134:137], v[150:153], v[126:129]
	v_mfma_f32_16x16x32_bf16 v[122:125], v[142:145], v[150:153], v[122:125]
	v_mfma_f32_16x16x32_bf16 v[110:113], v[134:137], v[158:161], v[110:113]
	v_mfma_f32_16x16x32_bf16 v[106:109], v[142:145], v[158:161], v[106:109]
	v_mfma_f32_16x16x32_bf16 v[94:97], v[134:137], v[166:169], v[94:97]
	v_mfma_f32_16x16x32_bf16 v[90:93], v[142:145], v[166:169], v[90:93]
	v_mfma_f32_16x16x32_bf16 v[78:81], v[134:137], v[174:177], v[78:81]
	v_mfma_f32_16x16x32_bf16 v[74:77], v[142:145], v[174:177], v[74:77]
	s_setprio 0
	s_barrier
	s_mov_b32 m0, s36
	v_lshl_add_u64 v[218:219], s[16:17], 0, v[182:183]
	ds_read_b128 v[196:199], v211
	ds_read_b128 v[200:203], v211 offset:1024
	ds_read_b128 v[204:207], v211 offset:2048
	ds_read_b128 v[214:217], v211 offset:3072
	global_load_lds_dwordx4 v[218:219], off
	v_lshl_add_u64 v[220:221], s[16:17], 0, v[178:179]
	s_mov_b32 m0, s37
	s_nop 0
	global_load_lds_dwordx4 v[220:221], off
	s_barrier
	s_waitcnt lgkmcnt(0)
	s_setprio 1
	s_waitcnt lgkmcnt(0)
	v_mfma_f32_16x16x32_bf16 v[118:121], v[196:199], v[146:149], v[118:121]
	v_mfma_f32_16x16x32_bf16 v[114:117], v[204:207], v[146:149], v[114:117]
	v_mfma_f32_16x16x32_bf16 v[102:105], v[196:199], v[154:157], v[102:105]
	v_mfma_f32_16x16x32_bf16 v[98:101], v[204:207], v[154:157], v[98:101]
	v_mfma_f32_16x16x32_bf16 v[86:89], v[196:199], v[162:165], v[86:89]
	v_mfma_f32_16x16x32_bf16 v[82:85], v[204:207], v[162:165], v[82:85]
	v_mfma_f32_16x16x32_bf16 v[70:73], v[196:199], v[170:173], v[70:73]
	v_mfma_f32_16x16x32_bf16 v[66:69], v[204:207], v[170:173], v[66:69]
	v_mfma_f32_16x16x32_bf16 v[118:121], v[200:203], v[150:153], v[118:121]
	v_mfma_f32_16x16x32_bf16 v[114:117], v[214:217], v[150:153], v[114:117]
	v_mfma_f32_16x16x32_bf16 v[102:105], v[200:203], v[158:161], v[102:105]
	v_mfma_f32_16x16x32_bf16 v[98:101], v[214:217], v[158:161], v[98:101]
	v_mfma_f32_16x16x32_bf16 v[86:89], v[200:203], v[166:169], v[86:89]
	v_mfma_f32_16x16x32_bf16 v[82:85], v[214:217], v[166:169], v[82:85]
	v_mfma_f32_16x16x32_bf16 v[70:73], v[200:203], v[174:177], v[70:73]
	v_mfma_f32_16x16x32_bf16 v[66:69], v[214:217], v[174:177], v[66:69]
	s_setprio 0
	s_mov_b32 m0, s3
	v_lshl_add_u64 v[222:223], s[18:19], 0, v[190:191]
	s_barrier
	ds_read_b128 v[146:149], v210 offset:16384
	ds_read_b128 v[150:153], v210 offset:17408
	ds_read_b128 v[154:157], v210 offset:18432
	ds_read_b128 v[158:161], v210 offset:19456
	ds_read_b128 v[162:165], v210 offset:20480
	ds_read_b128 v[166:169], v210 offset:21504
	ds_read_b128 v[170:173], v210 offset:22528
	ds_read_b128 v[174:177], v210 offset:23552
	global_load_lds_dwordx4 v[222:223], off
	v_lshl_add_u64 v[224:225], s[18:19], 0, v[180:181]
	s_mov_b32 m0, s20
	s_nop 0
	global_load_lds_dwordx4 v[224:225], off
	s_barrier
	s_waitcnt lgkmcnt(0)
	s_setprio 1
	s_waitcnt lgkmcnt(0)
	v_mfma_f32_16x16x32_bf16 v[62:65], v[130:133], v[146:149], v[62:65]
	v_mfma_f32_16x16x32_bf16 v[58:61], v[138:141], v[146:149], v[58:61]
	v_mfma_f32_16x16x32_bf16 v[46:49], v[130:133], v[154:157], v[46:49]
	v_mfma_f32_16x16x32_bf16 v[42:45], v[138:141], v[154:157], v[42:45]
	v_mfma_f32_16x16x32_bf16 v[30:33], v[130:133], v[162:165], v[30:33]
	v_mfma_f32_16x16x32_bf16 v[26:29], v[138:141], v[162:165], v[26:29]
	v_mfma_f32_16x16x32_bf16 v[14:17], v[130:133], v[170:173], v[14:17]
	v_mfma_f32_16x16x32_bf16 v[10:13], v[138:141], v[170:173], v[10:13]
	v_mfma_f32_16x16x32_bf16 v[62:65], v[134:137], v[150:153], v[62:65]
	v_mfma_f32_16x16x32_bf16 v[58:61], v[142:145], v[150:153], v[58:61]
	v_mfma_f32_16x16x32_bf16 v[46:49], v[134:137], v[158:161], v[46:49]
	v_mfma_f32_16x16x32_bf16 v[42:45], v[142:145], v[158:161], v[42:45]
	v_mfma_f32_16x16x32_bf16 v[30:33], v[134:137], v[166:169], v[30:33]
	v_mfma_f32_16x16x32_bf16 v[26:29], v[142:145], v[166:169], v[26:29]
	v_mfma_f32_16x16x32_bf16 v[14:17], v[134:137], v[174:177], v[14:17]
	v_mfma_f32_16x16x32_bf16 v[10:13], v[142:145], v[174:177], v[10:13]
	s_setprio 0
	s_barrier
	s_add_u32 s56, s16, 0x40000
	s_addc_u32 s57, s17, 0
	s_mov_b32 m0, s38
	v_lshl_add_u64 v[130:131], s[56:57], 0, v[182:183]
	global_load_lds_dwordx4 v[130:131], off
	v_lshl_add_u64 v[130:131], s[56:57], 0, v[178:179]
	s_mov_b32 m0, s39
	s_nop 0
	global_load_lds_dwordx4 v[130:131], off
	s_waitcnt vmcnt(6)
	s_barrier
	s_setprio 1
	v_mfma_f32_16x16x32_bf16 v[54:57], v[196:199], v[146:149], v[54:57]
	v_mfma_f32_16x16x32_bf16 v[50:53], v[204:207], v[146:149], v[50:53]
	v_mfma_f32_16x16x32_bf16 v[38:41], v[196:199], v[154:157], v[38:41]
	v_mfma_f32_16x16x32_bf16 v[34:37], v[204:207], v[154:157], v[34:37]
	v_mfma_f32_16x16x32_bf16 v[22:25], v[196:199], v[162:165], v[22:25]
	v_mfma_f32_16x16x32_bf16 v[18:21], v[204:207], v[162:165], v[18:21]
	v_mfma_f32_16x16x32_bf16 v[6:9], v[196:199], v[170:173], v[6:9]
	v_mfma_f32_16x16x32_bf16 v[2:5], v[204:207], v[170:173], v[2:5]
	v_mfma_f32_16x16x32_bf16 v[54:57], v[200:203], v[150:153], v[54:57]
	v_mfma_f32_16x16x32_bf16 v[50:53], v[214:217], v[150:153], v[50:53]
	v_mfma_f32_16x16x32_bf16 v[38:41], v[200:203], v[158:161], v[38:41]
	v_mfma_f32_16x16x32_bf16 v[34:37], v[214:217], v[158:161], v[34:37]
	v_mfma_f32_16x16x32_bf16 v[22:25], v[200:203], v[166:169], v[22:25]
	v_mfma_f32_16x16x32_bf16 v[18:21], v[214:217], v[166:169], v[18:21]
	v_mfma_f32_16x16x32_bf16 v[6:9], v[200:203], v[174:177], v[6:9]
	v_mfma_f32_16x16x32_bf16 v[2:5], v[214:217], v[174:177], v[2:5]
	s_setprio 0
	s_barrier
	ds_read_b128 v[130:133], v212
	ds_read_b128 v[134:137], v212 offset:1024
	ds_read_b128 v[138:141], v212 offset:2048
	ds_read_b128 v[142:145], v212 offset:3072
	s_add_u32 s18, s18, 0x40000
	s_addc_u32 s19, s19, 0
	s_mov_b32 m0, s21
	v_lshl_add_u64 v[196:197], s[18:19], 0, v[190:191]
	ds_read_b128 v[146:149], v210 offset:32768
	ds_read_b128 v[150:153], v210 offset:33792
	ds_read_b128 v[154:157], v210 offset:34816
	ds_read_b128 v[158:161], v210 offset:35840
	ds_read_b128 v[162:165], v210 offset:36864
	ds_read_b128 v[166:169], v210 offset:37888
	ds_read_b128 v[170:173], v210 offset:38912
	ds_read_b128 v[174:177], v210 offset:39936
	global_load_lds_dwordx4 v[196:197], off
	v_lshl_add_u64 v[196:197], s[18:19], 0, v[180:181]
	s_mov_b32 m0, s22
	s_nop 0
	global_load_lds_dwordx4 v[196:197], off
	s_waitcnt lgkmcnt(8)
	s_barrier
	s_waitcnt lgkmcnt(0)
	s_setprio 1
	s_waitcnt lgkmcnt(0)
	v_mfma_f32_16x16x32_bf16 v[126:129], v[130:133], v[146:149], v[126:129]
	v_mfma_f32_16x16x32_bf16 v[122:125], v[138:141], v[146:149], v[122:125]
	v_mfma_f32_16x16x32_bf16 v[110:113], v[130:133], v[154:157], v[110:113]
	v_mfma_f32_16x16x32_bf16 v[106:109], v[138:141], v[154:157], v[106:109]
	v_mfma_f32_16x16x32_bf16 v[94:97], v[130:133], v[162:165], v[94:97]
	v_mfma_f32_16x16x32_bf16 v[90:93], v[138:141], v[162:165], v[90:93]
	v_mfma_f32_16x16x32_bf16 v[78:81], v[130:133], v[170:173], v[78:81]
	v_mfma_f32_16x16x32_bf16 v[74:77], v[138:141], v[170:173], v[74:77]
	v_mfma_f32_16x16x32_bf16 v[126:129], v[134:137], v[150:153], v[126:129]
	v_mfma_f32_16x16x32_bf16 v[122:125], v[142:145], v[150:153], v[122:125]
	v_mfma_f32_16x16x32_bf16 v[110:113], v[134:137], v[158:161], v[110:113]
	v_mfma_f32_16x16x32_bf16 v[106:109], v[142:145], v[158:161], v[106:109]
	v_mfma_f32_16x16x32_bf16 v[94:97], v[134:137], v[166:169], v[94:97]
	v_mfma_f32_16x16x32_bf16 v[90:93], v[142:145], v[166:169], v[90:93]
	v_mfma_f32_16x16x32_bf16 v[78:81], v[134:137], v[174:177], v[78:81]
	v_mfma_f32_16x16x32_bf16 v[74:77], v[142:145], v[174:177], v[74:77]
	s_setprio 0
	s_barrier
	s_mov_b32 m0, s40
	v_lshl_add_u64 v[218:219], v[218:219], 0, s[0:1]
	ds_read_b128 v[196:199], v213
	ds_read_b128 v[200:203], v213 offset:1024
	ds_read_b128 v[204:207], v213 offset:2048
	ds_read_b128 v[214:217], v213 offset:3072
	global_load_lds_dwordx4 v[218:219], off
	v_lshl_add_u64 v[218:219], v[220:221], 0, s[0:1]
	s_mov_b32 m0, s41
	s_nop 0
	global_load_lds_dwordx4 v[218:219], off
	s_barrier
	s_waitcnt lgkmcnt(0)
	s_setprio 1
	s_waitcnt lgkmcnt(0)
	v_mfma_f32_16x16x32_bf16 v[118:121], v[196:199], v[146:149], v[118:121]
	v_mfma_f32_16x16x32_bf16 v[114:117], v[204:207], v[146:149], v[114:117]
	v_mfma_f32_16x16x32_bf16 v[102:105], v[196:199], v[154:157], v[102:105]
	v_mfma_f32_16x16x32_bf16 v[98:101], v[204:207], v[154:157], v[98:101]
	v_mfma_f32_16x16x32_bf16 v[86:89], v[196:199], v[162:165], v[86:89]
	v_mfma_f32_16x16x32_bf16 v[82:85], v[204:207], v[162:165], v[82:85]
	v_mfma_f32_16x16x32_bf16 v[70:73], v[196:199], v[170:173], v[70:73]
	v_mfma_f32_16x16x32_bf16 v[66:69], v[204:207], v[170:173], v[66:69]
	v_mfma_f32_16x16x32_bf16 v[118:121], v[200:203], v[150:153], v[118:121]
	v_mfma_f32_16x16x32_bf16 v[114:117], v[214:217], v[150:153], v[114:117]
	v_mfma_f32_16x16x32_bf16 v[102:105], v[200:203], v[158:161], v[102:105]
	v_mfma_f32_16x16x32_bf16 v[98:101], v[214:217], v[158:161], v[98:101]
	v_mfma_f32_16x16x32_bf16 v[86:89], v[200:203], v[166:169], v[86:89]
	v_mfma_f32_16x16x32_bf16 v[82:85], v[214:217], v[166:169], v[82:85]
	v_mfma_f32_16x16x32_bf16 v[70:73], v[200:203], v[174:177], v[70:73]
	v_mfma_f32_16x16x32_bf16 v[66:69], v[214:217], v[174:177], v[66:69]
	s_setprio 0
	s_mov_b32 m0, s30
	v_lshl_add_u64 v[218:219], v[222:223], 0, s[0:1]
	s_barrier
	ds_read_b128 v[146:149], v210 offset:49152
	ds_read_b128 v[150:153], v210 offset:50176
	ds_read_b128 v[154:157], v210 offset:51200
	ds_read_b128 v[158:161], v210 offset:52224
	ds_read_b128 v[162:165], v210 offset:53248
	ds_read_b128 v[166:169], v210 offset:54272
	ds_read_b128 v[170:173], v210 offset:55296
	ds_read_b128 v[174:177], v210 offset:56320
	global_load_lds_dwordx4 v[218:219], off
	v_lshl_add_u64 v[218:219], v[224:225], 0, s[0:1]
	s_mov_b32 m0, s31
	s_nop 0
	global_load_lds_dwordx4 v[218:219], off
	s_barrier
	s_waitcnt lgkmcnt(0)
	s_setprio 1
	s_waitcnt lgkmcnt(0)
	v_mfma_f32_16x16x32_bf16 v[62:65], v[130:133], v[146:149], v[62:65]
	v_mfma_f32_16x16x32_bf16 v[58:61], v[138:141], v[146:149], v[58:61]
	v_mfma_f32_16x16x32_bf16 v[46:49], v[130:133], v[154:157], v[46:49]
	v_mfma_f32_16x16x32_bf16 v[42:45], v[138:141], v[154:157], v[42:45]
	v_mfma_f32_16x16x32_bf16 v[30:33], v[130:133], v[162:165], v[30:33]
	v_mfma_f32_16x16x32_bf16 v[26:29], v[138:141], v[162:165], v[26:29]
	v_mfma_f32_16x16x32_bf16 v[14:17], v[130:133], v[170:173], v[14:17]
	v_mfma_f32_16x16x32_bf16 v[10:13], v[138:141], v[170:173], v[10:13]
	v_mfma_f32_16x16x32_bf16 v[62:65], v[134:137], v[150:153], v[62:65]
	v_mfma_f32_16x16x32_bf16 v[58:61], v[142:145], v[150:153], v[58:61]
	v_mfma_f32_16x16x32_bf16 v[46:49], v[134:137], v[158:161], v[46:49]
	v_mfma_f32_16x16x32_bf16 v[42:45], v[142:145], v[158:161], v[42:45]
	v_mfma_f32_16x16x32_bf16 v[30:33], v[134:137], v[166:169], v[30:33]
	v_mfma_f32_16x16x32_bf16 v[26:29], v[142:145], v[166:169], v[26:29]
	v_mfma_f32_16x16x32_bf16 v[14:17], v[134:137], v[174:177], v[14:17]
	v_mfma_f32_16x16x32_bf16 v[10:13], v[142:145], v[174:177], v[10:13]
	s_setprio 0
	s_barrier
	s_add_u32 s16, s16, s101
	s_addc_u32 s17, s17, 0
	s_mov_b32 m0, s42
	v_lshl_add_u64 v[130:131], s[16:17], 0, v[182:183]
	global_load_lds_dwordx4 v[130:131], off
	v_lshl_add_u64 v[130:131], s[16:17], 0, v[178:179]
	s_mov_b32 m0, s43
	s_nop 0
	global_load_lds_dwordx4 v[130:131], off
	s_waitcnt vmcnt(6)
	s_barrier
	s_setprio 1
	v_mfma_f32_16x16x32_bf16 v[54:57], v[196:199], v[146:149], v[54:57]
	v_mfma_f32_16x16x32_bf16 v[50:53], v[204:207], v[146:149], v[50:53]
	v_mfma_f32_16x16x32_bf16 v[38:41], v[196:199], v[154:157], v[38:41]
	v_mfma_f32_16x16x32_bf16 v[34:37], v[204:207], v[154:157], v[34:37]
	v_mfma_f32_16x16x32_bf16 v[22:25], v[196:199], v[162:165], v[22:25]
	v_mfma_f32_16x16x32_bf16 v[18:21], v[204:207], v[162:165], v[18:21]
	v_mfma_f32_16x16x32_bf16 v[6:9], v[196:199], v[170:173], v[6:9]
	v_mfma_f32_16x16x32_bf16 v[2:5], v[204:207], v[170:173], v[2:5]
	v_mfma_f32_16x16x32_bf16 v[54:57], v[200:203], v[150:153], v[54:57]
	v_mfma_f32_16x16x32_bf16 v[50:53], v[214:217], v[150:153], v[50:53]
	v_mfma_f32_16x16x32_bf16 v[38:41], v[200:203], v[158:161], v[38:41]
	v_mfma_f32_16x16x32_bf16 v[34:37], v[214:217], v[158:161], v[34:37]
	v_mfma_f32_16x16x32_bf16 v[22:25], v[200:203], v[166:169], v[22:25]
	v_mfma_f32_16x16x32_bf16 v[18:21], v[214:217], v[166:169], v[18:21]
	v_mfma_f32_16x16x32_bf16 v[6:9], v[200:203], v[174:177], v[6:9]
	v_mfma_f32_16x16x32_bf16 v[2:5], v[214:217], v[174:177], v[2:5]
	s_setprio 0
	s_add_i32 s54, s54, 2
	s_add_u32 s14, s14, s99
	s_addc_u32 s15, s15, s98
	s_cmp_gt_u32 s54, 13
	s_barrier
	s_cbranch_scc0 .LBB0_530
	v_mov_b32_e32 v130, v208
	v_mov_b32_e32 v215, v209
	s_lshl_b32 s14, s49, 8
	s_or_b32 s14, s14, s29
	v_add_u32_e32 v214, s28, v130
	v_add_u32_e32 v200, s44, v214
	v_lshl_add_u32 v196, v215, 3, s14
	v_ashrrev_i32_e32 v197, 31, v196
	v_ashrrev_i32_e32 v201, 31, v200
	v_lshl_add_u64 v[198:199], v[196:197], 2, s[60:61]
	v_lshlrev_b64 v[130:131], 12, v[200:201]
	v_lshl_add_u64 v[130:131], v[198:199], 0, v[130:131]
	global_load_dwordx4 v[216:219], v[130:131], off
	global_load_dwordx4 v[220:223], v[130:131], off offset:16
	global_load_dwordx4 v[224:227], v[130:131], off offset:512
	global_load_dwordx4 v[228:231], v[130:131], off offset:528
	v_add_u32_e32 v206, 16, v200
	v_add_u32_e32 v204, 32, v200
	v_add_u32_e32 v202, 48, v200
	v_ashrrev_i32_e32 v207, 31, v206
	v_ashrrev_i32_e32 v205, 31, v204
	v_ashrrev_i32_e32 v203, 31, v202
	v_lshlrev_b64 v[130:131], 12, v[206:207]
	v_lshlrev_b64 v[132:133], 12, v[204:205]
	v_lshlrev_b64 v[134:135], 12, v[202:203]
	v_lshl_add_u64 v[130:131], v[198:199], 0, v[130:131]
	v_lshl_add_u64 v[132:133], v[198:199], 0, v[132:133]
	v_lshl_add_u64 v[134:135], v[198:199], 0, v[134:135]
	global_load_dwordx4 v[170:173], v[130:131], off offset:16
	global_load_dwordx4 v[174:177], v[130:131], off
	global_load_dwordx4 v[162:165], v[130:131], off offset:528
	global_load_dwordx4 v[166:169], v[130:131], off offset:512
	global_load_dwordx4 v[154:157], v[132:133], off offset:16
	global_load_dwordx4 v[158:161], v[132:133], off
	global_load_dwordx4 v[146:149], v[132:133], off offset:528
	global_load_dwordx4 v[150:153], v[132:133], off offset:512
	global_load_dwordx4 v[138:141], v[134:135], off offset:16
	global_load_dwordx4 v[142:145], v[134:135], off
	s_nop 0
	global_load_dwordx4 v[130:133], v[134:135], off offset:528
	s_nop 0
	global_load_dwordx4 v[134:137], v[134:135], off offset:512
	v_lshlrev_b64 v[232:233], 11, v[200:201]
	v_cmp_eq_u32_e32 vcc, 0, v215
	s_waitcnt vmcnt(0)
	v_pk_add_f32 v[126:127], v[126:127], v[216:217]
	v_pk_add_f32 v[128:129], v[128:129], v[218:219]
	v_pk_add_f32 v[118:119], v[118:119], v[224:225]
	v_pk_add_f32 v[218:219], v[114:115], v[228:229]
	v_cvt_pk_bf16_f32 v114, v126, v127
	v_mul_f32_e32 v127, v127, v127
	v_mul_f32_e32 v201, v119, v119
	v_pk_add_f32 v[120:121], v[120:121], v[226:227]
	v_fmac_f32_e32 v127, v126, v126
	v_fmac_f32_e32 v201, v118, v118
	v_fmac_f32_e32 v127, v128, v128
	v_fmac_f32_e32 v201, v120, v120
	v_pk_add_f32 v[122:123], v[122:123], v[220:221]
	v_fmac_f32_e32 v127, v129, v129
	v_fmac_f32_e32 v201, v121, v121
	v_fmac_f32_e32 v127, v122, v122
	v_fmac_f32_e32 v201, v218, v218
	v_pk_add_f32 v[124:125], v[124:125], v[222:223]
	v_pk_add_f32 v[216:217], v[116:117], v[230:231]
	v_fmac_f32_e32 v127, v123, v123
	v_fmac_f32_e32 v201, v219, v219
	v_fmac_f32_e32 v127, v124, v124
	v_fmac_f32_e32 v201, v216, v216
	v_fmac_f32_e32 v127, v125, v125
	v_fmac_f32_e32 v201, v217, v217
	v_cvt_pk_bf16_f32 v117, v124, v125
	v_add_f32_e32 v124, v127, v201
	ds_bpermute_b32 v125, v187, v124
	v_cvt_pk_bf16_f32 v116, v122, v123
	v_lshl_add_u64 v[122:123], s[26:27], 0, v[232:233]
	v_cvt_pk_bf16_f32 v115, v128, v129
	v_lshl_add_u64 v[122:123], v[196:197], 1, v[122:123]
	global_store_dwordx4 v[122:123], v[114:117], off
	s_waitcnt lgkmcnt(0)
	s_nop 0
	v_add_f32_e32 v114, v124, v125
	ds_bpermute_b32 v115, v189, v114
	v_cvt_pk_bf16_f32 v116, v118, v119
	v_cvt_pk_bf16_f32 v117, v120, v121
	v_cvt_pk_bf16_f32 v118, v218, v219
	v_cvt_pk_bf16_f32 v119, v216, v217
	global_store_dwordx4 v[122:123], v[116:119], off offset:256
	s_and_saveexec_b64 s[14:15], vcc
	s_cbranch_execz .LBB0_533
	s_waitcnt lgkmcnt(0)
	v_add_f32_e32 v114, v114, v115
	v_lshl_add_u32 v115, v214, 2, 0
	v_add_u32_e32 v115, 0x20000, v115
	ds_add_f32 v115, v114
